# v105 + diff stage prefetch: 8 K/V loads in scalar-base + 32-bit lane-offset form (8 fewer 64-bit VALU adds per stage)
# baseline (speedup 1.0000x reference)
; #define DF_LOAD(T) do { const bf16* kg = Kb + (tokb + 128 * (T) + krow0) * 1024 + kgcol; const bf16* vg = Vb + (tokb + 128 * (T) + vkey0) * 1024 + vgcol; \
;         _Pragma("unroll") for (int c_ = 0; c_ < 4; ++c_) { kreg[c_] = *(const u32x4*)(kg + c_ * 8 * 1024); vreg[c_] = *(const u32x4*)(vg + c_ * 16 * 1024); } } while (0)
; __device__ __forceinline__ void diff_phase(LAS unsigned char* lds, int L) {
;     ...
;         for (int it = 0; it < NT; ++it) {
;             const int T = NT - 1 - it;
;             if (it + 1 < NT) DF_LOAD(T - 1);
.LBB0_186:
	s_cmp_lt_u32 s52, s35
	s_cselect_b64 s[30:31], -1, 0
	s_cmp_ge_u32 s52, s35
	s_cbranch_scc1 .LBB0_188
	s_add_u32 s44, s28, 0xe3c0000
	s_addc_u32 s45, s29, 0
	global_load_dwordx4 v[128:131], v190, s[44:45]
	s_add_u32 s44, s28, 0x123c0000
	s_addc_u32 s45, s29, 0
	global_load_dwordx4 v[132:135], v192, s[44:45]
	s_add_u32 s44, s28, 0xe3c4000
	s_addc_u32 s45, s29, 0
	global_load_dwordx4 v[140:143], v190, s[44:45]
	s_add_u32 s44, s28, 0x123c8000
	s_addc_u32 s45, s29, 0
	global_load_dwordx4 v[156:159], v192, s[44:45]
	s_add_u32 s44, s28, 0xe3c8000
	s_addc_u32 s45, s29, 0
	global_load_dwordx4 v[160:163], v190, s[44:45]
	s_add_u32 s44, s28, 0x123d0000
	s_addc_u32 s45, s29, 0
	global_load_dwordx4 v[164:167], v192, s[44:45]
	s_add_u32 s44, s28, 0xe3cc000
	s_addc_u32 s45, s29, 0
	global_load_dwordx4 v[168:171], v190, s[44:45]
	s_add_u32 s44, s28, 0x123d8000
	s_addc_u32 s45, s29, 0
	global_load_dwordx4 v[172:175], v192, s[44:45]
